# grid barrier release broadcast: last XCD leader bumps all XGEN words, other leaders poll XGEN directly (one hop less per barrier)
# speedup vs baseline: 1.0064x; 1.0045x over previous
; __device__ __forceinline__ unsigned xb_ld(unsigned* p)              { return __hip_atomic_load(p, __ATOMIC_RELAXED, __HIP_MEMORY_SCOPE_AGENT); }
; __device__ __forceinline__ unsigned xb_add(unsigned* p, unsigned v) { return __hip_atomic_fetch_add(p, v, __ATOMIC_RELAXED, __HIP_MEMORY_SCOPE_AGENT); }
; #define XB_SPIN(cond, bar) do { unsigned _sp = 0; while (cond) { __builtin_amdgcn_s_sleep(1); \
;     if ((++_sp & 255u) == 0u) { if (xb_ld(&(bar)[XB_TMO])) break; if (_sp > XB_SPIN_CAP) { atomicAdd(&(bar)[XB_TMO], 1u); break; } } } } while (0)
; __device__ __forceinline__ void xcd_barrier(const XcdBarrier& b) {
;     ...
;         const unsigned old = xb_add(&bar[XB_XSUB(b.x)], 1u);
;         const unsigned gen = old / nloc;
;         if (old + 1u == (gen + 1u) * nloc) {
;             __builtin_amdgcn_fence(__ATOMIC_RELEASE, "agent");
;             asm volatile("s_waitcnt vmcnt(0)" ::: "memory");
;             const unsigned og = xb_add(&bar[XB_TOP], 1u);
;             const unsigned tg = og / nx;
;             if (og + 1u == (tg + 1u) * nx) xb_add(&bar[XB_TOPGEN], 1u);
;             else XB_SPIN(xb_ld(&bar[XB_TOPGEN]) == tg, bar);
.LBB0_60:
	s_or_b64 exec, exec, s[8:9]
	v_cvt_f32_u32_e32 v4, v1
	s_waitcnt vmcnt(0)
	v_readfirstlane_b32 s6, v3
	s_add_u32 s8, s2, 0x4500
	s_addc_u32 s9, s3, 0
	v_rcp_iflag_f32_e32 v4, v4
	v_add_u32_e32 v2, s6, v2
	v_add_u32_e32 v5, 1, v2
	s_mov_b64 s[10:11], -1
	v_mul_f32_e32 v3, 0x4f7ffffe, v4
	v_cvt_u32_f32_e32 v3, v3
	v_sub_u32_e32 v4, 0, v1
	v_mul_lo_u32 v4, v4, v3
	v_mul_hi_u32 v4, v3, v4
	v_add_u32_e32 v3, v3, v4
	v_mul_hi_u32 v3, v2, v3
	v_mul_lo_u32 v4, v3, v1
	v_sub_u32_e32 v2, v2, v4
	v_add_u32_e32 v6, 1, v3
	v_cmp_ge_u32_e32 vcc, v2, v1
	v_sub_u32_e32 v4, v2, v1
	s_nop 0
	v_cndmask_b32_e32 v3, v3, v6, vcc
	v_cndmask_b32_e32 v2, v2, v4, vcc
	v_add_u32_e32 v4, 1, v3
	v_cmp_ge_u32_e32 vcc, v2, v1
	s_nop 1
	v_cndmask_b32_e32 v4, v3, v4, vcc
	v_mul_lo_u32 v2, v1, v4
	v_add_u32_e32 v1, v2, v1
	v_cmp_ne_u32_e32 vcc, v5, v1
	v_mov_b64_e32 v[2:3], s[8:9]
	s_and_saveexec_b64 s[6:7], vcc
	s_cbranch_execz .Lxb_last_9
	s_add_u32 s8, s4, 0x2400
	s_addc_u32 s9, s5, 0
	v_mov_b32_e32 v1, 0
	global_load_dword v2, v1, s[8:9] sc1
	s_mov_b64 s[14:15], 0
	s_waitcnt vmcnt(0)
	v_cmp_eq_u32_e32 vcc, v2, v4
	s_and_saveexec_b64 s[12:13], vcc
	s_cbranch_execz .LBB0_71
	s_add_u32 s10, s2, 0x1200
	s_addc_u32 s11, s3, 0
	s_mov_b32 s22, 1
	s_mov_b64 s[2:3], 0
	s_branch .LBB0_64

; __device__ __forceinline__ unsigned xb_ld(unsigned* p)              { return __hip_atomic_load(p, __ATOMIC_RELAXED, __HIP_MEMORY_SCOPE_AGENT); }
; __device__ __forceinline__ unsigned xb_add(unsigned* p, unsigned v) { return __hip_atomic_fetch_add(p, v, __ATOMIC_RELAXED, __HIP_MEMORY_SCOPE_AGENT); }
; #define XB_SPIN(cond, bar) do { unsigned _sp = 0; while (cond) { __builtin_amdgcn_s_sleep(1); \
;     if ((++_sp & 255u) == 0u) { if (xb_ld(&(bar)[XB_TMO])) break; if (_sp > XB_SPIN_CAP) { atomicAdd(&(bar)[XB_TMO], 1u); break; } } } } while (0)
; __device__ __forceinline__ void xcd_barrier(const XcdBarrier& b) {
;     ...
;             if (og + 1u == (tg + 1u) * nx) xb_add(&bar[XB_TOPGEN], 1u);
;             else XB_SPIN(xb_ld(&bar[XB_TOPGEN]) == tg, bar);
;             __builtin_amdgcn_fence(__ATOMIC_ACQUIRE, "agent");
;             xb_add(&bar[XB_XGEN(b.x)], 1u);
.LBB0_71:
	s_or_b64 exec, exec, s[12:13]
	v_mov_b64_e32 v[2:3], s[10:11]
	s_orn2_b64 s[10:11], s[14:15], exec
	s_branch .LBB0_72
.Lxb_last_9:
	s_or_b64 exec, exec, s[6:7]
	v_mov_b32_e32 v5, 0x3400
	v_mov_b32_e32 v6, 1
	global_atomic_add v5, v6, s[2:3]
	global_atomic_add v5, v6, s[2:3] offset:256
	global_atomic_add v5, v6, s[2:3] offset:512
	global_atomic_add v5, v6, s[2:3] offset:768
	global_atomic_add v5, v6, s[2:3] offset:1024
	global_atomic_add v5, v6, s[2:3] offset:1280
	global_atomic_add v5, v6, s[2:3] offset:1536
	global_atomic_add v5, v6, s[2:3] offset:1792
	global_atomic_add v5, v6, s[2:3] offset:2048
	global_atomic_add v5, v6, s[2:3] offset:2304
	global_atomic_add v5, v6, s[2:3] offset:2560
	global_atomic_add v5, v6, s[2:3] offset:2816
	global_atomic_add v5, v6, s[2:3] offset:3072
	global_atomic_add v5, v6, s[2:3] offset:3328
	global_atomic_add v5, v6, s[2:3] offset:3584
	global_atomic_add v5, v6, s[2:3] offset:3840

; __device__ __forceinline__ unsigned xb_add(unsigned* p, unsigned v) { return __hip_atomic_fetch_add(p, v, __ATOMIC_RELAXED, __HIP_MEMORY_SCOPE_AGENT); }
; __device__ __forceinline__ void xcd_barrier(const XcdBarrier& b) {
;     ...
;             __builtin_amdgcn_fence(__ATOMIC_ACQUIRE, "agent");
;             xb_add(&bar[XB_XGEN(b.x)], 1u);
;             asm volatile("s_waitcnt vmcnt(0)" ::: "memory");
.LBB0_74:
	s_or_b64 exec, exec, s[2:3]
	s_mov_b64 s[2:3], exec
	v_mbcnt_lo_u32_b32 v1, s2, 0
	v_mbcnt_hi_u32_b32 v1, s3, v1
	v_cmp_eq_u32_e32 vcc, 0, v1
	s_waitcnt vmcnt(0)
	buffer_inv sc1
	s_and_saveexec_b64 s[6:7], vcc
	s_cbranch_execz .LBB0_76
	s_bcnt1_i32_b64 s2, s[2:3]
	v_mov_b32_e32 v1, 0x2000
	v_mov_b32_e32 v2, s2
.LBB0_76:
	s_or_b64 exec, exec, s[6:7]
	s_waitcnt vmcnt(0)

; __device__ __forceinline__ unsigned xb_ld(unsigned* p)              { return __hip_atomic_load(p, __ATOMIC_RELAXED, __HIP_MEMORY_SCOPE_AGENT); }
; __device__ __forceinline__ unsigned xb_add(unsigned* p, unsigned v) { return __hip_atomic_fetch_add(p, v, __ATOMIC_RELAXED, __HIP_MEMORY_SCOPE_AGENT); }
; #define XB_SPIN(cond, bar) do { unsigned _sp = 0; while (cond) { __builtin_amdgcn_s_sleep(1); \
;     if ((++_sp & 255u) == 0u) { if (xb_ld(&(bar)[XB_TMO])) break; if (_sp > XB_SPIN_CAP) { atomicAdd(&(bar)[XB_TMO], 1u); break; } } } } while (0)
; __device__ __forceinline__ void xcd_barrier(const XcdBarrier& b) {
;     ...
;         const unsigned old = xb_add(&bar[XB_XSUB(b.x)], 1u);
;         const unsigned gen = old / nloc;
;         if (old + 1u == (gen + 1u) * nloc) {
;             __builtin_amdgcn_fence(__ATOMIC_RELEASE, "agent");
;             asm volatile("s_waitcnt vmcnt(0)" ::: "memory");
;             const unsigned og = xb_add(&bar[XB_TOP], 1u);
;             const unsigned tg = og / nx;
;             if (og + 1u == (tg + 1u) * nx) xb_add(&bar[XB_TOPGEN], 1u);
;             else XB_SPIN(xb_ld(&bar[XB_TOPGEN]) == tg, bar);
.LBB0_154:
	s_or_b64 exec, exec, s[10:11]
	v_cvt_f32_u32_e32 v5, v2
	s_waitcnt vmcnt(0)
	v_readfirstlane_b32 s8, v4
	s_mov_b64 s[12:13], -1
	v_rcp_iflag_f32_e32 v5, v5
	v_add_u32_e32 v3, s8, v3
	v_add_u32_e32 v6, 1, v3
	s_add_u32 s8, s2, 0x4500
	v_mul_f32_e32 v4, 0x4f7ffffe, v5
	v_cvt_u32_f32_e32 v4, v4
	v_sub_u32_e32 v5, 0, v2
	s_addc_u32 s9, s3, 0
	v_mul_lo_u32 v5, v5, v4
	v_mul_hi_u32 v5, v4, v5
	v_add_u32_e32 v4, v4, v5
	v_mul_hi_u32 v4, v3, v4
	v_mul_lo_u32 v5, v4, v2
	v_sub_u32_e32 v3, v3, v5
	v_add_u32_e32 v7, 1, v4
	v_cmp_ge_u32_e32 vcc, v3, v2
	v_sub_u32_e32 v5, v3, v2
	s_nop 0
	v_cndmask_b32_e32 v4, v4, v7, vcc
	v_cndmask_b32_e32 v3, v3, v5, vcc
	v_add_u32_e32 v5, 1, v4
	v_cmp_ge_u32_e32 vcc, v3, v2
	s_nop 1
	v_cndmask_b32_e32 v4, v4, v5, vcc
	v_mul_lo_u32 v3, v2, v4
	v_add_u32_e32 v2, v3, v2
	v_cmp_ne_u32_e32 vcc, v6, v2
	v_mov_b64_e32 v[2:3], s[8:9]
	s_and_saveexec_b64 s[10:11], vcc
	s_cbranch_execz .Lxb_last_8
	s_add_u32 s8, s4, 0x2400
	s_addc_u32 s9, s5, 0
	global_load_dword v2, v35, s[8:9] sc1
	s_mov_b64 s[18:19], 0
	s_waitcnt vmcnt(0)
	v_cmp_eq_u32_e32 vcc, v2, v4
	s_and_saveexec_b64 s[16:17], vcc
	s_cbranch_execz .LBB0_165
	s_add_u32 s12, s2, 0x1200
	s_addc_u32 s13, s3, 0
	s_mov_b32 s26, 1
	s_mov_b64 s[2:3], 0
	s_branch .LBB0_158

; __device__ __forceinline__ unsigned xb_ld(unsigned* p)              { return __hip_atomic_load(p, __ATOMIC_RELAXED, __HIP_MEMORY_SCOPE_AGENT); }
; __device__ __forceinline__ unsigned xb_add(unsigned* p, unsigned v) { return __hip_atomic_fetch_add(p, v, __ATOMIC_RELAXED, __HIP_MEMORY_SCOPE_AGENT); }
; #define XB_SPIN(cond, bar) do { unsigned _sp = 0; while (cond) { __builtin_amdgcn_s_sleep(1); \
;     if ((++_sp & 255u) == 0u) { if (xb_ld(&(bar)[XB_TMO])) break; if (_sp > XB_SPIN_CAP) { atomicAdd(&(bar)[XB_TMO], 1u); break; } } } } while (0)
; __device__ __forceinline__ void xcd_barrier(const XcdBarrier& b) {
;     ...
;             if (og + 1u == (tg + 1u) * nx) xb_add(&bar[XB_TOPGEN], 1u);
;             else XB_SPIN(xb_ld(&bar[XB_TOPGEN]) == tg, bar);
;             __builtin_amdgcn_fence(__ATOMIC_ACQUIRE, "agent");
;             xb_add(&bar[XB_XGEN(b.x)], 1u);
.LBB0_165:
	s_or_b64 exec, exec, s[16:17]
	v_mov_b64_e32 v[2:3], s[12:13]
	s_orn2_b64 s[12:13], s[18:19], exec
	s_branch .LBB0_166
.Lxb_last_8:
	s_or_b64 exec, exec, s[10:11]
	v_mov_b32_e32 v5, 0x3400
	v_mov_b32_e32 v6, 1
	global_atomic_add v5, v6, s[2:3]
	global_atomic_add v5, v6, s[2:3] offset:256
	global_atomic_add v5, v6, s[2:3] offset:512
	global_atomic_add v5, v6, s[2:3] offset:768
	global_atomic_add v5, v6, s[2:3] offset:1024
	global_atomic_add v5, v6, s[2:3] offset:1280
	global_atomic_add v5, v6, s[2:3] offset:1536
	global_atomic_add v5, v6, s[2:3] offset:1792
	global_atomic_add v5, v6, s[2:3] offset:2048
	global_atomic_add v5, v6, s[2:3] offset:2304
	global_atomic_add v5, v6, s[2:3] offset:2560
	global_atomic_add v5, v6, s[2:3] offset:2816
	global_atomic_add v5, v6, s[2:3] offset:3072
	global_atomic_add v5, v6, s[2:3] offset:3328
	global_atomic_add v5, v6, s[2:3] offset:3584
	global_atomic_add v5, v6, s[2:3] offset:3840

; __device__ __forceinline__ unsigned xb_add(unsigned* p, unsigned v) { return __hip_atomic_fetch_add(p, v, __ATOMIC_RELAXED, __HIP_MEMORY_SCOPE_AGENT); }
; __device__ __forceinline__ void xcd_barrier(const XcdBarrier& b) {
;     ...
;             __builtin_amdgcn_fence(__ATOMIC_ACQUIRE, "agent");
;             xb_add(&bar[XB_XGEN(b.x)], 1u);
;             asm volatile("s_waitcnt vmcnt(0)" ::: "memory");
.LBB0_168:
	s_or_b64 exec, exec, s[2:3]
	s_mov_b64 s[2:3], exec
	v_mbcnt_lo_u32_b32 v2, s2, 0
	v_mbcnt_hi_u32_b32 v2, s3, v2
	v_cmp_eq_u32_e32 vcc, 0, v2
	s_waitcnt vmcnt(0)
	buffer_inv sc1
	s_and_saveexec_b64 s[8:9], vcc
	s_cbranch_execz .LBB0_170
	s_bcnt1_i32_b64 s2, s[2:3]
	v_mov_b32_e32 v2, s2
	v_mov_b32_e32 v3, 0x2000
.LBB0_170:
	s_or_b64 exec, exec, s[8:9]
	s_waitcnt vmcnt(0)

; __device__ __forceinline__ unsigned xb_add(unsigned* p, unsigned v) { return __hip_atomic_fetch_add(p, v, __ATOMIC_RELAXED, __HIP_MEMORY_SCOPE_AGENT); }
; __device__ __forceinline__ void xcd_barrier(const XcdBarrier& b) {
;     ...
;             __builtin_amdgcn_fence(__ATOMIC_ACQUIRE, "agent");
;             xb_add(&bar[XB_XGEN(b.x)], 1u);
;             asm volatile("s_waitcnt vmcnt(0)" ::: "memory");
.LBB0_242:
	s_or_b64 exec, exec, s[2:3]
	s_mov_b64 s[2:3], exec
	v_mbcnt_lo_u32_b32 v2, s2, 0
	v_mbcnt_hi_u32_b32 v2, s3, v2
	v_cmp_eq_u32_e32 vcc, 0, v2
	s_waitcnt vmcnt(0)
	buffer_inv sc1
	s_and_saveexec_b64 s[8:9], vcc
	s_cbranch_execz .LBB0_244
	s_bcnt1_i32_b64 s2, s[2:3]
	v_mov_b32_e32 v2, s2
	v_mov_b32_e32 v3, 0x2000
.LBB0_244:
	s_or_b64 exec, exec, s[8:9]
	s_waitcnt vmcnt(0)

; __device__ __forceinline__ unsigned xb_ld(unsigned* p)              { return __hip_atomic_load(p, __ATOMIC_RELAXED, __HIP_MEMORY_SCOPE_AGENT); }
; __device__ __forceinline__ unsigned xb_add(unsigned* p, unsigned v) { return __hip_atomic_fetch_add(p, v, __ATOMIC_RELAXED, __HIP_MEMORY_SCOPE_AGENT); }
; #define XB_SPIN(cond, bar) do { unsigned _sp = 0; while (cond) { __builtin_amdgcn_s_sleep(1); \
;     if ((++_sp & 255u) == 0u) { if (xb_ld(&(bar)[XB_TMO])) break; if (_sp > XB_SPIN_CAP) { atomicAdd(&(bar)[XB_TMO], 1u); break; } } } } while (0)
; __device__ __forceinline__ void xcd_barrier(const XcdBarrier& b) {
;     ...
;         const unsigned old = xb_add(&bar[XB_XSUB(b.x)], 1u);
;         const unsigned gen = old / nloc;
;         if (old + 1u == (gen + 1u) * nloc) {
;             __builtin_amdgcn_fence(__ATOMIC_RELEASE, "agent");
;             asm volatile("s_waitcnt vmcnt(0)" ::: "memory");
;             const unsigned og = xb_add(&bar[XB_TOP], 1u);
;             const unsigned tg = og / nx;
;             if (og + 1u == (tg + 1u) * nx) xb_add(&bar[XB_TOPGEN], 1u);
;             else XB_SPIN(xb_ld(&bar[XB_TOPGEN]) == tg, bar);
.LBB0_335:
	s_or_b64 exec, exec, s[8:9]
	s_waitcnt vmcnt(0)
	v_readfirstlane_b32 s6, v4
	v_cvt_f32_u32_e32 v4, v2
	v_sub_u32_e32 v5, 0, v2
	v_add_u32_e32 v3, s6, v3
	s_add_u32 s6, s2, 0x4500
	v_rcp_iflag_f32_e32 v4, v4
	s_addc_u32 s7, s3, 0
	s_mov_b64 s[10:11], -1
	v_mul_f32_e32 v4, 0x4f7ffffe, v4
	v_cvt_u32_f32_e32 v4, v4
	v_mul_lo_u32 v5, v5, v4
	v_mul_hi_u32 v5, v4, v5
	v_add_u32_e32 v4, v4, v5
	v_mul_hi_u32 v4, v3, v4
	v_mul_lo_u32 v5, v4, v2
	v_sub_u32_e32 v5, v3, v5
	v_cmp_ge_u32_e32 vcc, v5, v2
	v_add_u32_e32 v6, 1, v4
	v_add_u32_e32 v3, 1, v3
	v_cndmask_b32_e32 v4, v4, v6, vcc
	v_sub_u32_e32 v6, v5, v2
	v_cndmask_b32_e32 v5, v5, v6, vcc
	v_cmp_ge_u32_e32 vcc, v5, v2
	v_add_u32_e32 v5, 1, v4
	s_nop 0
	v_cndmask_b32_e32 v4, v4, v5, vcc
	v_mul_lo_u32 v5, v2, v4
	v_add_u32_e32 v2, v5, v2
	v_cmp_ne_u32_e32 vcc, v3, v2
	v_mov_b64_e32 v[2:3], s[6:7]
	s_and_saveexec_b64 s[8:9], vcc
	s_cbranch_execz .Lxb_last_6
	s_add_u32 s6, s4, 0x2400
	s_addc_u32 s7, s5, 0
	global_load_dword v2, v35, s[6:7] sc1
	s_mov_b64 s[14:15], 0
	s_waitcnt vmcnt(0)
	v_cmp_eq_u32_e32 vcc, v2, v4
	s_and_saveexec_b64 s[12:13], vcc
	s_cbranch_execz .LBB0_346
	s_add_u32 s10, s2, 0x1200
	s_addc_u32 s11, s3, 0
	s_mov_b32 s22, 1
	s_mov_b64 s[2:3], 0
	s_branch .LBB0_339

; __device__ __forceinline__ unsigned xb_ld(unsigned* p)              { return __hip_atomic_load(p, __ATOMIC_RELAXED, __HIP_MEMORY_SCOPE_AGENT); }
; __device__ __forceinline__ unsigned xb_add(unsigned* p, unsigned v) { return __hip_atomic_fetch_add(p, v, __ATOMIC_RELAXED, __HIP_MEMORY_SCOPE_AGENT); }
; #define XB_SPIN(cond, bar) do { unsigned _sp = 0; while (cond) { __builtin_amdgcn_s_sleep(1); \
;     if ((++_sp & 255u) == 0u) { if (xb_ld(&(bar)[XB_TMO])) break; if (_sp > XB_SPIN_CAP) { atomicAdd(&(bar)[XB_TMO], 1u); break; } } } } while (0)
; __device__ __forceinline__ void xcd_barrier(const XcdBarrier& b) {
;     ...
;             if (og + 1u == (tg + 1u) * nx) xb_add(&bar[XB_TOPGEN], 1u);
;             else XB_SPIN(xb_ld(&bar[XB_TOPGEN]) == tg, bar);
;             __builtin_amdgcn_fence(__ATOMIC_ACQUIRE, "agent");
;             xb_add(&bar[XB_XGEN(b.x)], 1u);
.Lxb_last_6:
	s_or_b64 exec, exec, s[8:9]
	v_mov_b32_e32 v5, 0x3400
	v_mov_b32_e32 v6, 1
	global_atomic_add v5, v6, s[2:3]
	global_atomic_add v5, v6, s[2:3] offset:256
	global_atomic_add v5, v6, s[2:3] offset:512
	global_atomic_add v5, v6, s[2:3] offset:768
	global_atomic_add v5, v6, s[2:3] offset:1024
	global_atomic_add v5, v6, s[2:3] offset:1280
	global_atomic_add v5, v6, s[2:3] offset:1536
	global_atomic_add v5, v6, s[2:3] offset:1792
	global_atomic_add v5, v6, s[2:3] offset:2048
	global_atomic_add v5, v6, s[2:3] offset:2304
	global_atomic_add v5, v6, s[2:3] offset:2560
	global_atomic_add v5, v6, s[2:3] offset:2816
	global_atomic_add v5, v6, s[2:3] offset:3072
	global_atomic_add v5, v6, s[2:3] offset:3328
	global_atomic_add v5, v6, s[2:3] offset:3584
	global_atomic_add v5, v6, s[2:3] offset:3840

; __device__ __forceinline__ unsigned xb_add(unsigned* p, unsigned v) { return __hip_atomic_fetch_add(p, v, __ATOMIC_RELAXED, __HIP_MEMORY_SCOPE_AGENT); }
; __device__ __forceinline__ void xcd_barrier(const XcdBarrier& b) {
;     ...
;             __builtin_amdgcn_fence(__ATOMIC_ACQUIRE, "agent");
;             xb_add(&bar[XB_XGEN(b.x)], 1u);
;             asm volatile("s_waitcnt vmcnt(0)" ::: "memory");
.LBB0_349:
	s_or_b64 exec, exec, s[2:3]
	s_mov_b64 s[2:3], exec
	v_mbcnt_lo_u32_b32 v2, s2, 0
	v_mbcnt_hi_u32_b32 v2, s3, v2
	v_cmp_eq_u32_e32 vcc, 0, v2
	s_waitcnt vmcnt(0)
	buffer_inv sc1
	s_and_saveexec_b64 s[6:7], vcc
	s_cbranch_execz .LBB0_351
	s_bcnt1_i32_b64 s2, s[2:3]
	v_mov_b32_e32 v2, s2
	v_mov_b32_e32 v3, 0x2000
.LBB0_351:
	s_or_b64 exec, exec, s[6:7]
	s_waitcnt vmcnt(0)

; __device__ __forceinline__ unsigned xb_add(unsigned* p, unsigned v) { return __hip_atomic_fetch_add(p, v, __ATOMIC_RELAXED, __HIP_MEMORY_SCOPE_AGENT); }
; __device__ __forceinline__ void xcd_barrier(const XcdBarrier& b) {
;     ...
;             __builtin_amdgcn_fence(__ATOMIC_ACQUIRE, "agent");
;             xb_add(&bar[XB_XGEN(b.x)], 1u);
;             asm volatile("s_waitcnt vmcnt(0)" ::: "memory");
.LBB0_442:
	s_or_b64 exec, exec, s[2:3]
	s_mov_b64 s[2:3], exec
	v_mbcnt_lo_u32_b32 v2, s2, 0
	v_mbcnt_hi_u32_b32 v2, s3, v2
	v_cmp_eq_u32_e32 vcc, 0, v2
	s_waitcnt vmcnt(0)
	buffer_inv sc1
	s_and_saveexec_b64 s[6:7], vcc
	s_cbranch_execz .LBB0_444
	s_bcnt1_i32_b64 s2, s[2:3]
	v_mov_b32_e32 v2, s2
	v_mov_b32_e32 v3, 0x2000
.LBB0_444:
	s_or_b64 exec, exec, s[6:7]
	s_waitcnt vmcnt(0)

; __device__ __forceinline__ unsigned xb_add(unsigned* p, unsigned v) { return __hip_atomic_fetch_add(p, v, __ATOMIC_RELAXED, __HIP_MEMORY_SCOPE_AGENT); }
; __device__ __forceinline__ void xcd_barrier(const XcdBarrier& b) {
;     ...
;             __builtin_amdgcn_fence(__ATOMIC_ACQUIRE, "agent");
;             xb_add(&bar[XB_XGEN(b.x)], 1u);
;             asm volatile("s_waitcnt vmcnt(0)" ::: "memory");
.LBB0_526:
	s_or_b64 exec, exec, s[2:3]
	s_mov_b64 s[2:3], exec
	v_mbcnt_lo_u32_b32 v2, s2, 0
	v_mbcnt_hi_u32_b32 v2, s3, v2
	v_cmp_eq_u32_e32 vcc, 0, v2
	s_waitcnt vmcnt(0)
	buffer_inv sc1
	s_and_saveexec_b64 s[6:7], vcc
	s_cbranch_execz .LBB0_528
	s_bcnt1_i32_b64 s2, s[2:3]
	v_mov_b32_e32 v2, s2
	v_mov_b32_e32 v3, 0x2000
.LBB0_528:
	s_or_b64 exec, exec, s[6:7]
	s_waitcnt vmcnt(0)

; __device__ __forceinline__ unsigned xb_add(unsigned* p, unsigned v) { return __hip_atomic_fetch_add(p, v, __ATOMIC_RELAXED, __HIP_MEMORY_SCOPE_AGENT); }
; __device__ __forceinline__ void xcd_barrier(const XcdBarrier& b) {
;     ...
;             __builtin_amdgcn_fence(__ATOMIC_ACQUIRE, "agent");
;             xb_add(&bar[XB_XGEN(b.x)], 1u);
;             asm volatile("s_waitcnt vmcnt(0)" ::: "memory");
.LBB0_610:
	s_or_b64 exec, exec, s[2:3]
	s_mov_b64 s[2:3], exec
	v_mbcnt_lo_u32_b32 v2, s2, 0
	v_mbcnt_hi_u32_b32 v2, s3, v2
	v_cmp_eq_u32_e32 vcc, 0, v2
	s_waitcnt vmcnt(0)
	buffer_inv sc1
	s_and_saveexec_b64 s[6:7], vcc
	s_cbranch_execz .LBB0_612
	s_bcnt1_i32_b64 s2, s[2:3]
	v_mov_b32_e32 v2, s2
	v_mov_b32_e32 v3, 0x2000
.LBB0_612:
	s_or_b64 exec, exec, s[6:7]
	s_waitcnt vmcnt(0)

; __device__ __forceinline__ unsigned xb_ld(unsigned* p)              { return __hip_atomic_load(p, __ATOMIC_RELAXED, __HIP_MEMORY_SCOPE_AGENT); }
; __device__ __forceinline__ unsigned xb_add(unsigned* p, unsigned v) { return __hip_atomic_fetch_add(p, v, __ATOMIC_RELAXED, __HIP_MEMORY_SCOPE_AGENT); }
; #define XB_SPIN(cond, bar) do { unsigned _sp = 0; while (cond) { __builtin_amdgcn_s_sleep(1); \
;     if ((++_sp & 255u) == 0u) { if (xb_ld(&(bar)[XB_TMO])) break; if (_sp > XB_SPIN_CAP) { atomicAdd(&(bar)[XB_TMO], 1u); break; } } } } while (0)
; __device__ __forceinline__ void xcd_barrier(const XcdBarrier& b) {
;     ...
;         const unsigned old = xb_add(&bar[XB_XSUB(b.x)], 1u);
;         const unsigned gen = old / nloc;
;         if (old + 1u == (gen + 1u) * nloc) {
;             __builtin_amdgcn_fence(__ATOMIC_RELEASE, "agent");
;             asm volatile("s_waitcnt vmcnt(0)" ::: "memory");
;             const unsigned og = xb_add(&bar[XB_TOP], 1u);
;             const unsigned tg = og / nx;
;             if (og + 1u == (tg + 1u) * nx) xb_add(&bar[XB_TOPGEN], 1u);
;             else XB_SPIN(xb_ld(&bar[XB_TOPGEN]) == tg, bar);
.LBB0_658:
	s_or_b64 exec, exec, s[10:11]
	s_waitcnt vmcnt(0)
	v_readfirstlane_b32 s8, v4
	v_cvt_f32_u32_e32 v4, v2
	v_sub_u32_e32 v5, 0, v2
	v_add_u32_e32 v3, s8, v3
	s_add_u32 s8, s2, 0x4500
	v_rcp_iflag_f32_e32 v4, v4
	s_addc_u32 s9, s3, 0
	s_mov_b64 s[12:13], -1
	v_mul_f32_e32 v4, 0x4f7ffffe, v4
	v_cvt_u32_f32_e32 v4, v4
	v_mul_lo_u32 v5, v5, v4
	v_mul_hi_u32 v5, v4, v5
	v_add_u32_e32 v4, v4, v5
	v_mul_hi_u32 v4, v3, v4
	v_mul_lo_u32 v5, v4, v2
	v_sub_u32_e32 v5, v3, v5
	v_cmp_ge_u32_e32 vcc, v5, v2
	v_add_u32_e32 v6, 1, v4
	v_add_u32_e32 v3, 1, v3
	v_cndmask_b32_e32 v4, v4, v6, vcc
	v_sub_u32_e32 v6, v5, v2
	v_cndmask_b32_e32 v5, v5, v6, vcc
	v_cmp_ge_u32_e32 vcc, v5, v2
	v_add_u32_e32 v5, 1, v4
	s_nop 0
	v_cndmask_b32_e32 v4, v4, v5, vcc
	v_mul_lo_u32 v5, v2, v4
	v_add_u32_e32 v2, v5, v2
	v_cmp_ne_u32_e32 vcc, v3, v2
	v_mov_b64_e32 v[2:3], s[8:9]
	s_and_saveexec_b64 s[10:11], vcc
	s_cbranch_execz .Lxb_last_2
	s_add_u32 s8, s4, 0x2400
	s_addc_u32 s9, s5, 0
	global_load_dword v2, v35, s[8:9] sc1
	s_mov_b64 s[16:17], 0
	s_waitcnt vmcnt(0)
	v_cmp_eq_u32_e32 vcc, v2, v4
	s_and_saveexec_b64 s[14:15], vcc
	s_cbranch_execz .LBB0_669
	s_add_u32 s12, s2, 0x1200
	s_addc_u32 s13, s3, 0
	s_mov_b32 s24, 1
	s_mov_b64 s[2:3], 0
	s_branch .LBB0_662

; __device__ __forceinline__ unsigned xb_ld(unsigned* p)              { return __hip_atomic_load(p, __ATOMIC_RELAXED, __HIP_MEMORY_SCOPE_AGENT); }
; __device__ __forceinline__ unsigned xb_add(unsigned* p, unsigned v) { return __hip_atomic_fetch_add(p, v, __ATOMIC_RELAXED, __HIP_MEMORY_SCOPE_AGENT); }
; #define XB_SPIN(cond, bar) do { unsigned _sp = 0; while (cond) { __builtin_amdgcn_s_sleep(1); \
;     if ((++_sp & 255u) == 0u) { if (xb_ld(&(bar)[XB_TMO])) break; if (_sp > XB_SPIN_CAP) { atomicAdd(&(bar)[XB_TMO], 1u); break; } } } } while (0)
; __device__ __forceinline__ void xcd_barrier(const XcdBarrier& b) {
;     ...
;             if (og + 1u == (tg + 1u) * nx) xb_add(&bar[XB_TOPGEN], 1u);
;             else XB_SPIN(xb_ld(&bar[XB_TOPGEN]) == tg, bar);
;             __builtin_amdgcn_fence(__ATOMIC_ACQUIRE, "agent");
;             xb_add(&bar[XB_XGEN(b.x)], 1u);
.LBB0_669:
	s_or_b64 exec, exec, s[14:15]
	v_mov_b64_e32 v[2:3], s[12:13]
	s_orn2_b64 s[12:13], s[16:17], exec
	s_branch .LBB0_670

; __device__ __forceinline__ unsigned xb_add(unsigned* p, unsigned v) { return __hip_atomic_fetch_add(p, v, __ATOMIC_RELAXED, __HIP_MEMORY_SCOPE_AGENT); }
; __device__ __forceinline__ void xcd_barrier(const XcdBarrier& b) {
;     ...
;             __builtin_amdgcn_fence(__ATOMIC_ACQUIRE, "agent");
;             xb_add(&bar[XB_XGEN(b.x)], 1u);
;             asm volatile("s_waitcnt vmcnt(0)" ::: "memory");
.LBB0_672:
	s_or_b64 exec, exec, s[2:3]
	s_mov_b64 s[2:3], exec
	v_mbcnt_lo_u32_b32 v2, s2, 0
	v_mbcnt_hi_u32_b32 v2, s3, v2
	v_cmp_eq_u32_e32 vcc, 0, v2
	s_waitcnt vmcnt(0)
	buffer_inv sc1
	s_and_saveexec_b64 s[8:9], vcc
	s_cbranch_execz .LBB0_674
	s_bcnt1_i32_b64 s2, s[2:3]
	v_mov_b32_e32 v2, s2
	v_mov_b32_e32 v3, 0x2000
.LBB0_674:
	s_or_b64 exec, exec, s[8:9]
	s_waitcnt vmcnt(0)

; __device__ __forceinline__ unsigned xb_add(unsigned* p, unsigned v) { return __hip_atomic_fetch_add(p, v, __ATOMIC_RELAXED, __HIP_MEMORY_SCOPE_AGENT); }
; __device__ __forceinline__ void xcd_barrier(const XcdBarrier& b) {
;     ...
;             __builtin_amdgcn_fence(__ATOMIC_ACQUIRE, "agent");
;             xb_add(&bar[XB_XGEN(b.x)], 1u);
;             asm volatile("s_waitcnt vmcnt(0)" ::: "memory");
.LBB0_969:
	s_or_b64 exec, exec, s[2:3]
	s_mov_b64 s[2:3], exec
	v_mbcnt_lo_u32_b32 v2, s2, 0
	v_mbcnt_hi_u32_b32 v2, s3, v2
	v_cmp_eq_u32_e32 vcc, 0, v2
	s_waitcnt vmcnt(0)
	buffer_inv sc1
	s_and_saveexec_b64 s[8:9], vcc
	s_cbranch_execz .LBB0_971
	s_bcnt1_i32_b64 s2, s[2:3]
	v_mov_b32_e32 v2, s2
	v_mov_b32_e32 v3, 0x2000
.LBB0_971:
	s_or_b64 exec, exec, s[8:9]
	s_waitcnt vmcnt(0)

; __device__ __forceinline__ unsigned xb_add(unsigned* p, unsigned v) { return __hip_atomic_fetch_add(p, v, __ATOMIC_RELAXED, __HIP_MEMORY_SCOPE_AGENT); }
; __device__ __forceinline__ void xcd_barrier(const XcdBarrier& b) {
;     ...
;             __builtin_amdgcn_fence(__ATOMIC_ACQUIRE, "agent");
;             xb_add(&bar[XB_XGEN(b.x)], 1u);
;             asm volatile("s_waitcnt vmcnt(0)" ::: "memory");
.LBB0_1064:
	s_bcnt1_i32_b64 s2, s[2:3]
	v_mov_b32_e32 v2, s2
	v_mov_b32_e32 v3, 0x2000
	s_getpc_b64 s[98:99]
